# v123 plus a vmcnt(0) after the wait-side cache invalidate on the sample-hit path (the invalidate completes before the workgroup barrier releases the next phase's loads)
# baseline (speedup 1.0000x reference)
.Lsb0_done:
	s_or_b64 exec, exec, s[16:17]
	s_waitcnt vmcnt(0)
	s_barrier
